# FFN-up G (and raw-row) stores non-temporal
# speedup vs baseline: 1.0329x; 1.0329x over previous
.LBB0_1165:
	s_or_b64 exec, exec, s[34:35]
	s_waitcnt vmcnt(0)
	ds_write2st64_b32 v217, v130, v131 offset1:8
	s_waitcnt vmcnt(0) lgkmcnt(0)
	s_barrier
	v_or_b32_e32 v188, s2, v193
	v_ashrrev_i32_e32 v189, 31, v188
	s_and_saveexec_b64 s[2:3], s[96:97]
	s_xor_b64 s[34:35], exec, s[2:3]
	s_andn2_saveexec_b64 s[34:35], s[34:35]
	s_cbranch_execz .LBB0_1167
	s_ashr_i32 s23, s22, 31
	v_readlane_b32 s60, v252, 48
	s_lshl_b64 s[2:3], s[22:23], 2
	v_cndmask_b32_e64 v130, 2, 0, s[46:47]
	v_readlane_b32 s61, v252, 49
	v_or_b32_e32 v132, s2, v130
	s_mov_b32 s2, 0xb000
	v_mov_b64_e32 v[130:131], s[60:61]
	v_mad_u64_u32 v[130:131], s[60:61], v132, s2, v[130:131]
	v_mov_b32_e32 v132, 0xb000
	v_mad_i32_i24 v131, s3, v132, v131
	v_lshl_add_u64 v[134:135], v[188:189], 2, v[130:131]
	v_cndmask_b32_e64 v133, v87, v129, s[46:47]
	v_cndmask_b32_e64 v132, v86, v128, s[46:47]
	v_cndmask_b32_e64 v131, v85, v127, s[46:47]
	v_cndmask_b32_e64 v130, v84, v126, s[46:47]
	v_add_co_u32_e32 v136, vcc, s2, v134
	global_store_dwordx4 v[134:135], v[130:133], off nt
	s_nop 0
	v_addc_co_u32_e32 v137, vcc, 0, v135, vcc
	v_cndmask_b32_e64 v133, v83, v125, s[46:47]
	v_cndmask_b32_e64 v132, v82, v124, s[46:47]
	v_cndmask_b32_e64 v131, v81, v123, s[46:47]
	v_cndmask_b32_e64 v130, v80, v122, s[46:47]
	global_store_dwordx4 v[136:137], v[130:133], off nt
	s_movk_i32 s2, 0x5000
	s_nop 0
	v_cndmask_b32_e64 v133, v19, v59, s[46:47]
	v_cndmask_b32_e64 v132, v18, v58, s[46:47]
	v_cndmask_b32_e64 v131, v17, v57, s[46:47]
	v_cndmask_b32_e64 v130, v16, v56, s[46:47]
	global_store_dwordx4 v[134:135], v[130:133], off offset:16 nt
	s_nop 1
	v_cndmask_b32_e64 v133, v23, v55, s[46:47]
	v_cndmask_b32_e64 v132, v22, v54, s[46:47]
	v_cndmask_b32_e64 v131, v21, v53, s[46:47]
	v_cndmask_b32_e64 v130, v20, v52, s[46:47]
	global_store_dwordx4 v[136:137], v[130:133], off offset:16 nt
	v_add_co_u32_e32 v136, vcc, s2, v134
	s_mov_b32 s2, 0x10000
	s_nop 0
	v_addc_co_u32_e32 v137, vcc, 0, v135, vcc
	v_cndmask_b32_e64 v133, v71, v113, s[46:47]
	v_cndmask_b32_e64 v132, v70, v112, s[46:47]
	v_cndmask_b32_e64 v131, v69, v111, s[46:47]
	v_cndmask_b32_e64 v130, v68, v110, s[46:47]
	v_add_co_u32_e32 v134, vcc, s2, v134
	global_store_dwordx4 v[136:137], v[130:133], off offset:2048 nt
	s_nop 0
	v_addc_co_u32_e32 v135, vcc, 0, v135, vcc
	v_cndmask_b32_e64 v133, v67, v109, s[46:47]
	v_cndmask_b32_e64 v132, v66, v108, s[46:47]
	v_cndmask_b32_e64 v131, v65, v107, s[46:47]
	v_cndmask_b32_e64 v130, v64, v106, s[46:47]
	global_store_dwordx4 v[134:135], v[130:133], off offset:2048 nt
	s_nop 1
	v_cndmask_b32_e64 v133, v3, v43, s[46:47]
	v_cndmask_b32_e64 v132, v2, v42, s[46:47]
	v_cndmask_b32_e64 v131, v1, v41, s[46:47]
	v_cndmask_b32_e64 v130, v0, v40, s[46:47]
	global_store_dwordx4 v[136:137], v[130:133], off offset:2064 nt
	s_nop 1
	v_cndmask_b32_e64 v133, v7, v39, s[46:47]
	v_cndmask_b32_e64 v132, v6, v38, s[46:47]
	v_cndmask_b32_e64 v131, v5, v37, s[46:47]
	v_cndmask_b32_e64 v130, v4, v36, s[46:47]
	global_store_dwordx4 v[134:135], v[130:133], off offset:2064 nt

.LBB0_1179:
	s_waitcnt lgkmcnt(5)
	v_cndmask_b32_e64 v78, v78, v140, s[48:49]
	v_cndmask_b32_e64 v79, v79, v141, s[48:49]
	v_pk_mul_f32 v[78:79], v[102:103], v[78:79]
	v_cndmask_b32_e64 v94, v94, v138, s[48:49]
	v_pk_fma_f32 v[78:79], v[58:59], v[128:129], v[78:79]
	v_cndmask_b32_e64 v95, v95, v139, s[48:49]
	v_pk_fma_f32 v[78:79], v[54:55], v[120:121], v[78:79]
	v_pk_mul_f32 v[94:95], v[100:101], v[94:95]
	v_pk_add_f32 v[116:117], v[124:125], v[78:79]
	v_pk_fma_f32 v[94:95], v[56:57], v[126:127], v[94:95]
	v_mul_f32_e32 v78, 0xbfb8aa3b, v116
	v_exp_f32_e32 v78, v78
	v_mul_f32_e32 v79, 0xbfb8aa3b, v117
	v_exp_f32_e32 v79, v79
	v_pk_fma_f32 v[94:95], v[52:53], v[118:119], v[94:95]
	v_add_f32_e32 v78, 1.0, v78
	v_pk_add_f32 v[108:109], v[122:123], v[94:95]
	v_rcp_f32_e32 v142, v78
	v_mul_f32_e32 v94, 0xbfb8aa3b, v108
	v_exp_f32_e32 v94, v94
	v_mul_f32_e32 v95, 0xbfb8aa3b, v109
	v_add_f32_e32 v78, 1.0, v79
	v_mov_b32_e32 v79, v97
	v_exp_f32_e32 v95, v95
	v_add_f32_e32 v94, 1.0, v94
	v_mov_b32_dpp v79, v32 row_ror:1 row_mask:0xf bank_mask:0xf
	s_waitcnt lgkmcnt(0)
	v_cndmask_b32_e64 v134, v79, v134, s[48:49]
	v_mov_b32_e32 v79, v97
	v_mov_b32_e32 v105, v97
	v_rcp_f32_e32 v112, v94
	v_mov_b32_dpp v79, v33 row_ror:1 row_mask:0xf bank_mask:0xf
	v_cndmask_b32_e64 v135, v79, v135, s[48:49]
	v_mov_b32_e32 v79, v97
	v_add_f32_e32 v94, 1.0, v95
	v_mov_b32_dpp v105, v35 row_ror:1 row_mask:0xf bank_mask:0xf
	v_mov_b32_dpp v79, v34 row_ror:1 row_mask:0xf bank_mask:0xf
	v_rcp_f32_e32 v113, v94
	v_rcp_f32_e32 v143, v78
	ds_read_b128 v[138:141], v220 offset:48
	v_cndmask_b32_e64 v136, v79, v136, s[48:49]
	v_cndmask_b32_e64 v137, v105, v137, s[48:49]
	v_pk_mul_f32 v[136:137], v[88:89], v[136:137]
	v_pk_mul_f32 v[134:135], v[86:87], v[134:135]
	v_pk_fma_f32 v[136:137], v[42:43], v[92:93], v[136:137]
	v_pk_fma_f32 v[134:135], v[40:41], v[90:91], v[134:135]
	v_mov_b32_e32 v78, v97
	v_mov_b32_e32 v94, v97
	v_mov_b32_e32 v95, v97
	v_mov_b32_e32 v79, v97
	v_pk_fma_f32 v[136:137], v[38:39], v[84:85], v[136:137]
	v_pk_fma_f32 v[134:135], v[36:37], v[82:83], v[134:135]
	s_lshl_b32 s2, s22, 8
	v_mov_b32_dpp v78, v40 row_ror:15 row_mask:0xf bank_mask:0xf
	v_mov_b32_dpp v94, v41 row_ror:15 row_mask:0xf bank_mask:0xf
	v_mov_b32_dpp v95, v42 row_ror:15 row_mask:0xf bank_mask:0xf
	v_mov_b32_dpp v79, v43 row_ror:15 row_mask:0xf bank_mask:0xf
	v_pk_add_f32 v[134:135], v[66:67], v[134:135]
	v_pk_add_f32 v[136:137], v[68:69], v[136:137]
	v_pk_mul_f32 v[108:109], v[108:109], v[112:113]
	v_pk_mul_f32 v[112:113], v[116:117], v[142:143]
	v_pk_mul_f32 v[108:109], v[108:109], v[134:135]
	v_pk_mul_f32 v[112:113], v[112:113], v[136:137]
	v_cvt_pk_bf16_f32 v116, v108, v109
	s_nop 0
	v_cvt_pk_bf16_f32 v117, v112, v113
	s_and_saveexec_b64 s[22:23], s[50:51]
	s_movk_i32 s3, 0x2c00
	s_cbranch_execz .LBB0_1181
	v_add_u32_e32 v105, s2, v194
	v_mov_b64_e32 v[108:109], s[88:89]
	v_mad_i64_i32 v[108:109], s[34:35], v105, s3, v[108:109]
	v_lshl_add_u64 v[108:109], v[188:189], 1, v[108:109]
	global_store_dwordx4 v[108:109], v[114:117], off nt
.LBB0_1181:
	s_or_b64 exec, exec, s[22:23]
	v_pk_mul_f32 v[108:109], v[54:55], v[128:129]
	v_pk_mul_f32 v[112:113], v[60:61], v[126:127]
	v_pk_fma_f32 v[58:59], v[58:59], v[102:103], v[108:109]
	s_waitcnt lgkmcnt(0)
	v_cndmask_b32_e64 v114, v78, v138, s[44:45]
	v_pk_fma_f32 v[58:59], v[62:63], v[120:121], v[58:59]
	v_cndmask_b32_e64 v115, v94, v139, s[44:45]
	v_pk_add_f32 v[58:59], v[124:125], v[58:59]
	v_cndmask_b32_e64 v78, v95, v140, s[44:45]
	v_mul_f32_e32 v105, 0xbfb8aa3b, v58
	v_exp_f32_e32 v105, v105
	v_mul_f32_e32 v108, 0xbfb8aa3b, v59
	v_exp_f32_e32 v109, v108
	v_pk_mul_f32 v[94:95], v[52:53], v[126:127]
	v_pk_fma_f32 v[52:53], v[52:53], v[100:101], v[112:113]
	v_add_f32_e32 v105, 1.0, v105
	v_pk_fma_f32 v[52:53], v[44:45], v[118:119], v[52:53]
	v_pk_fma_f32 v[56:57], v[56:57], v[100:101], v[94:95]
	v_pk_add_f32 v[52:53], v[122:123], v[52:53]
	v_rcp_f32_e32 v108, v105
	v_add_f32_e32 v105, 1.0, v109
	v_mul_f32_e32 v109, 0xbfb8aa3b, v52
	v_pk_fma_f32 v[56:57], v[60:61], v[118:119], v[56:57]
	v_exp_f32_e32 v112, v109
	v_mul_f32_e32 v109, 0xbfb8aa3b, v53
	v_pk_add_f32 v[56:57], v[122:123], v[56:57]
	v_exp_f32_e32 v113, v109
	v_mul_f32_e32 v94, 0xbfb8aa3b, v56
	v_mul_f32_e32 v95, 0xbfb8aa3b, v57
	v_exp_f32_e32 v94, v94
	v_exp_f32_e32 v95, v95
	v_rcp_f32_e32 v109, v105
	v_add_f32_e32 v105, 1.0, v112
	v_rcp_f32_e32 v116, v105
	v_add_f32_e32 v105, 1.0, v113
	v_pk_mul_f32 v[112:113], v[62:63], v[128:129]
	v_add_f32_e32 v94, 1.0, v94
	v_pk_fma_f32 v[54:55], v[54:55], v[102:103], v[112:113]
	v_add_f32_e32 v95, 1.0, v95
	v_pk_fma_f32 v[54:55], v[46:47], v[120:121], v[54:55]
	v_pk_mul_f32 v[44:45], v[44:45], v[126:127]
	v_rcp_f32_e32 v94, v94
	v_rcp_f32_e32 v95, v95
	v_pk_add_f32 v[54:55], v[124:125], v[54:55]
	v_cndmask_b32_e64 v75, v75, v131, s[44:45]
	v_cndmask_b32_e64 v74, v74, v130, s[44:45]
	v_pk_fma_f32 v[44:45], v[60:61], v[100:101], v[44:45]
	v_pk_mul_f32 v[46:47], v[46:47], v[128:129]
	v_mul_f32_e32 v112, 0xbfb8aa3b, v54
	v_pk_fma_f32 v[44:45], v[118:119], v[74:75], v[44:45]
	v_cndmask_b32_e64 v71, v71, v133, s[44:45]
	v_cndmask_b32_e64 v70, v70, v132, s[44:45]
	v_pk_fma_f32 v[46:47], v[62:63], v[102:103], v[46:47]
	v_pk_mul_f32 v[74:75], v[36:37], v[90:91]
	v_exp_f32_e32 v112, v112
	v_mul_f32_e32 v113, 0xbfb8aa3b, v55
	v_pk_fma_f32 v[46:47], v[120:121], v[70:71], v[46:47]
	v_pk_mul_f32 v[70:71], v[38:39], v[92:93]
	v_pk_fma_f32 v[40:41], v[40:41], v[86:87], v[74:75]
	v_exp_f32_e32 v113, v113
	v_pk_fma_f32 v[42:43], v[42:43], v[88:89], v[70:71]
	v_pk_fma_f32 v[40:41], v[48:49], v[82:83], v[40:41]
	v_pk_fma_f32 v[42:43], v[50:51], v[84:85], v[42:43]
	v_pk_add_f32 v[40:41], v[66:67], v[40:41]
	v_pk_mul_f32 v[56:57], v[56:57], v[94:95]
	v_pk_add_f32 v[42:43], v[68:69], v[42:43]
	v_pk_mul_f32 v[58:59], v[58:59], v[108:109]
	v_pk_mul_f32 v[40:41], v[56:57], v[40:41]
	v_rcp_f32_e32 v117, v105
	v_add_f32_e32 v105, 1.0, v112
	v_pk_mul_f32 v[42:43], v[58:59], v[42:43]
	v_cvt_pk_bf16_f32 v112, v40, v41
	v_or_b32_e32 v40, 1, v194
	v_rcp_f32_e32 v134, v105
	v_add_f32_e32 v105, 1.0, v113
	v_cvt_pk_bf16_f32 v113, v42, v43
	v_add_u32_e32 v42, s2, v40
	v_mov_b64_e32 v[40:41], s[88:89]
	v_mad_i64_i32 v[42:43], s[22:23], v42, s3, v[40:41]
	v_lshlrev_b64 v[70:71], 1, v[188:189]
	v_pk_mul_f32 v[56:57], v[48:49], v[90:91]
	v_pk_add_f32 v[44:45], v[122:123], v[44:45]
	v_pk_add_f32 v[46:47], v[124:125], v[46:47]
	v_lshl_add_u64 v[42:43], v[42:43], 0, v[70:71]
	v_pk_fma_f32 v[36:37], v[36:37], v[86:87], v[56:57]
	v_mul_f32_e32 v60, 0xbfb8aa3b, v44
	v_mul_f32_e32 v61, 0xbfb8aa3b, v45
	v_mul_f32_e32 v62, 0xbfb8aa3b, v46
	v_mul_f32_e32 v63, 0xbfb8aa3b, v47
	global_store_dwordx4 v[42:43], v[110:113], off nt
	v_pk_mul_f32 v[42:43], v[50:51], v[92:93]
	v_pk_fma_f32 v[36:37], v[32:33], v[82:83], v[36:37]
	v_exp_f32_e32 v60, v60
	v_exp_f32_e32 v61, v61
	v_exp_f32_e32 v62, v62
	v_exp_f32_e32 v63, v63
	v_pk_fma_f32 v[38:39], v[38:39], v[88:89], v[42:43]
	v_pk_add_f32 v[36:37], v[66:67], v[36:37]
	v_pk_mul_f32 v[42:43], v[52:53], v[116:117]
	v_rcp_f32_e32 v135, v105
	v_pk_mul_f32 v[36:37], v[42:43], v[36:37]
	v_add_f32_e32 v60, 1.0, v60
	v_cvt_pk_bf16_f32 v108, v36, v37
	v_or_b32_e32 v36, 2, v194
	v_add_u32_e32 v36, s2, v36
	v_add_f32_e32 v61, 1.0, v61
	v_add_f32_e32 v62, 1.0, v62
	v_add_f32_e32 v63, 1.0, v63
	v_pk_fma_f32 v[38:39], v[34:35], v[84:85], v[38:39]
	v_mad_i64_i32 v[36:37], s[22:23], v36, s3, v[40:41]
	v_rcp_f32_e32 v60, v60
	v_rcp_f32_e32 v61, v61
	v_rcp_f32_e32 v62, v62
	v_rcp_f32_e32 v63, v63
	v_pk_add_f32 v[38:39], v[68:69], v[38:39]
	v_pk_mul_f32 v[52:53], v[54:55], v[134:135]
	v_lshl_add_u64 v[36:37], v[36:37], 0, v[70:71]
	v_pk_mul_f32 v[38:39], v[52:53], v[38:39]
	v_pk_mul_f32 v[34:35], v[34:35], v[92:93]
	v_cvt_pk_bf16_f32 v109, v38, v39
	global_store_dwordx4 v[36:37], v[106:109], off nt
	v_pk_mul_f32 v[32:33], v[32:33], v[90:91]
	v_cndmask_b32_e64 v79, v79, v141, s[44:45]
	v_pk_fma_f32 v[34:35], v[50:51], v[88:89], v[34:35]
	v_pk_fma_f32 v[32:33], v[48:49], v[86:87], v[32:33]
	v_pk_fma_f32 v[34:35], v[84:85], v[78:79], v[34:35]
	v_pk_fma_f32 v[32:33], v[82:83], v[114:115], v[32:33]
	v_pk_add_f32 v[34:35], v[68:69], v[34:35]
	v_pk_add_f32 v[32:33], v[66:67], v[32:33]
	v_pk_mul_f32 v[36:37], v[44:45], v[60:61]
	v_pk_mul_f32 v[38:39], v[46:47], v[62:63]
	v_pk_mul_f32 v[32:33], v[36:37], v[32:33]
	v_pk_mul_f32 v[34:35], v[38:39], v[34:35]
	v_cvt_pk_bf16_f32 v100, v32, v33
	s_nop 0
	v_cvt_pk_bf16_f32 v101, v34, v35
	s_and_saveexec_b64 s[22:23], s[52:53]
	s_cbranch_execz .LBB0_1183
	v_or_b32_e32 v32, 3, v194
	v_add_u32_e32 v34, s2, v32
	v_mov_b64_e32 v[32:33], s[88:89]
	v_mad_i64_i32 v[32:33], s[34:35], v34, s3, v[32:33]
	v_lshl_add_u64 v[32:33], v[188:189], 1, v[32:33]
	global_store_dwordx4 v[32:33], v[98:101], off nt

.LBB0_1187:
	s_waitcnt lgkmcnt(5)
	v_cndmask_b32_e64 v93, v99, v93, s[48:49]
	v_cndmask_b32_e64 v92, v98, v92, s[48:49]
	v_pk_mul_f32 v[92:93], v[60:61], v[92:93]
	v_cndmask_b32_e64 v83, v83, v95, s[48:49]
	v_pk_fma_f32 v[92:93], v[24:25], v[56:57], v[92:93]
	v_cndmask_b32_e64 v82, v82, v94, s[48:49]
	v_pk_fma_f32 v[92:93], v[28:29], v[48:49], v[92:93]
	v_pk_mul_f32 v[82:83], v[62:63], v[82:83]
	v_pk_add_f32 v[98:99], v[52:53], v[92:93]
	v_pk_fma_f32 v[82:83], v[26:27], v[58:59], v[82:83]
	v_mul_f32_e32 v92, 0xbfb8aa3b, v98
	v_exp_f32_e32 v92, v92
	v_mul_f32_e32 v93, 0xbfb8aa3b, v99
	v_exp_f32_e32 v93, v93
	v_pk_fma_f32 v[82:83], v[30:31], v[50:51], v[82:83]
	v_add_f32_e32 v92, 1.0, v92
	v_pk_add_f32 v[82:83], v[54:55], v[82:83]
	v_rcp_f32_e32 v100, v92
	v_add_f32_e32 v92, 1.0, v93
	v_mul_f32_e32 v93, 0xbfb8aa3b, v82
	v_exp_f32_e32 v93, v93
	v_mul_f32_e32 v94, 0xbfb8aa3b, v83
	v_rcp_f32_e32 v101, v92
	v_exp_f32_e32 v95, v94
	v_add_f32_e32 v92, 1.0, v93
	v_mov_b32_e32 v93, v97
	v_mov_b32_e32 v104, v97
	v_rcp_f32_e32 v94, v92
	v_mov_b32_dpp v93, v4 row_ror:1 row_mask:0xf bank_mask:0xf
	s_waitcnt lgkmcnt(0)
	v_cndmask_b32_e64 v102, v93, v88, s[48:49]
	v_mov_b32_e32 v88, v97
	v_add_f32_e32 v92, 1.0, v95
	v_mov_b32_dpp v104, v7 row_ror:1 row_mask:0xf bank_mask:0xf
	v_mov_b32_dpp v88, v5 row_ror:1 row_mask:0xf bank_mask:0xf
	v_cndmask_b32_e64 v103, v88, v89, s[48:49]
	v_mov_b32_e32 v88, v97
	v_rcp_f32_e32 v95, v92
	v_cndmask_b32_e64 v91, v104, v91, s[48:49]
	v_mov_b32_dpp v88, v6 row_ror:1 row_mask:0xf bank_mask:0xf
	v_cndmask_b32_e64 v90, v88, v90, s[48:49]
	v_pk_mul_f32 v[90:91], v[46:47], v[90:91]
	v_pk_mul_f32 v[102:103], v[44:45], v[102:103]
	v_pk_fma_f32 v[90:91], v[14:15], v[42:43], v[90:91]
	v_pk_fma_f32 v[102:103], v[12:13], v[40:41], v[102:103]
	v_pk_fma_f32 v[90:91], v[10:11], v[38:39], v[90:91]
	v_pk_fma_f32 v[102:103], v[8:9], v[36:37], v[102:103]
	v_mov_b32_e32 v92, v97
	v_mov_b32_e32 v93, v97
	v_mov_b32_e32 v89, v97
	v_mov_b32_e32 v88, v97
	v_pk_add_f32 v[102:103], v[32:33], v[102:103]
	v_pk_add_f32 v[90:91], v[34:35], v[90:91]
	v_pk_mul_f32 v[98:99], v[98:99], v[100:101]
	v_pk_mul_f32 v[82:83], v[82:83], v[94:95]
	v_mov_b32_dpp v92, v12 row_ror:15 row_mask:0xf bank_mask:0xf
	v_mov_b32_dpp v93, v13 row_ror:15 row_mask:0xf bank_mask:0xf
	v_mov_b32_dpp v89, v14 row_ror:15 row_mask:0xf bank_mask:0xf
	v_mov_b32_dpp v88, v15 row_ror:15 row_mask:0xf bank_mask:0xf
	v_pk_mul_f32 v[90:91], v[82:83], v[90:91]
	v_pk_mul_f32 v[82:83], v[98:99], v[102:103]
	s_nop 0
	v_cvt_pk_bf16_f32 v82, v82, v83
	v_cvt_pk_bf16_f32 v83, v90, v91
	s_and_saveexec_b64 s[22:23], s[54:55]
	s_cbranch_execz .LBB0_1189
	v_add_u32_e32 v90, 0x80, v194
	v_add_u32_e32 v94, s2, v90
	v_mov_b64_e32 v[90:91], s[88:89]
	v_mad_i64_i32 v[90:91], s[34:35], v94, s3, v[90:91]
	v_lshl_add_u64 v[90:91], v[188:189], 1, v[90:91]
	global_store_dwordx4 v[90:91], v[80:83], off nt
.LBB0_1189:
	s_or_b64 exec, exec, s[22:23]
	s_nop 0
	v_cndmask_b32_e64 v80, v92, v84, s[44:45]
	v_cndmask_b32_e64 v81, v93, v85, s[44:45]
	v_pk_mul_f32 v[84:85], v[28:29], v[56:57]
	v_cndmask_b32_e64 v82, v89, v86, s[44:45]
	v_pk_fma_f32 v[24:25], v[24:25], v[60:61], v[84:85]
	v_pk_mul_f32 v[90:91], v[18:19], v[58:59]
	v_pk_fma_f32 v[24:25], v[16:17], v[48:49], v[24:25]
	v_cndmask_b32_e64 v66, v78, v66, s[44:45]
	v_pk_add_f32 v[24:25], v[52:53], v[24:25]
	v_cndmask_b32_e64 v67, v79, v67, s[44:45]
	v_mul_f32_e32 v83, 0xbfb8aa3b, v24
	v_exp_f32_e32 v84, v83
	v_mul_f32_e32 v83, 0xbfb8aa3b, v25
	v_exp_f32_e32 v85, v83
	v_cndmask_b32_e64 v83, v88, v87, s[44:45]
	v_pk_mul_f32 v[86:87], v[30:31], v[58:59]
	v_pk_mul_f32 v[88:89], v[16:17], v[56:57]
	v_pk_fma_f32 v[26:27], v[26:27], v[62:63], v[86:87]
	v_pk_fma_f32 v[28:29], v[28:29], v[60:61], v[88:89]
	v_pk_fma_f32 v[26:27], v[18:19], v[50:51], v[26:27]
	v_pk_fma_f32 v[28:29], v[20:21], v[48:49], v[28:29]
	v_pk_add_f32 v[26:27], v[54:55], v[26:27]
	v_pk_fma_f32 v[30:31], v[30:31], v[62:63], v[90:91]
	v_mul_f32_e32 v86, 0xbfb8aa3b, v26
	v_mul_f32_e32 v87, 0xbfb8aa3b, v27
	v_exp_f32_e32 v86, v86
	v_exp_f32_e32 v87, v87
	v_pk_mul_f32 v[20:21], v[20:21], v[56:57]
	v_add_f32_e32 v84, 1.0, v84
	v_add_f32_e32 v85, 1.0, v85
	v_pk_fma_f32 v[30:31], v[22:23], v[50:51], v[30:31]
	v_pk_fma_f32 v[16:17], v[16:17], v[60:61], v[20:21]
	v_pk_mul_f32 v[22:23], v[22:23], v[58:59]
	v_rcp_f32_e32 v84, v84
	v_rcp_f32_e32 v85, v85
	v_add_f32_e32 v86, 1.0, v86
	v_add_f32_e32 v87, 1.0, v87
	v_pk_add_f32 v[28:29], v[52:53], v[28:29]
	v_pk_fma_f32 v[16:17], v[48:49], v[66:67], v[16:17]
	v_cndmask_b32_e64 v48, v74, v68, s[44:45]
	v_cndmask_b32_e64 v49, v75, v69, s[44:45]
	v_pk_fma_f32 v[18:19], v[18:19], v[62:63], v[22:23]
	v_rcp_f32_e32 v86, v86
	v_mul_f32_e32 v88, 0xbfb8aa3b, v28
	v_mul_f32_e32 v89, 0xbfb8aa3b, v29
	v_rcp_f32_e32 v87, v87
	v_pk_fma_f32 v[18:19], v[50:51], v[48:49], v[18:19]
	v_pk_mul_f32 v[50:51], v[8:9], v[40:41]
	v_exp_f32_e32 v88, v88
	v_exp_f32_e32 v89, v89
	v_pk_mul_f32 v[48:49], v[10:11], v[42:43]
	v_pk_fma_f32 v[12:13], v[12:13], v[44:45], v[50:51]
	v_pk_fma_f32 v[14:15], v[14:15], v[46:47], v[48:49]
	v_pk_fma_f32 v[12:13], v[0:1], v[36:37], v[12:13]
	v_pk_add_f32 v[30:31], v[54:55], v[30:31]
	v_pk_fma_f32 v[14:15], v[2:3], v[38:39], v[14:15]
	v_pk_add_f32 v[12:13], v[32:33], v[12:13]
	v_pk_mul_f32 v[24:25], v[24:25], v[84:85]
	v_mul_f32_e32 v90, 0xbfb8aa3b, v30
	v_mul_f32_e32 v91, 0xbfb8aa3b, v31
	v_pk_add_f32 v[14:15], v[34:35], v[14:15]
	v_pk_mul_f32 v[26:27], v[26:27], v[86:87]
	v_pk_mul_f32 v[12:13], v[24:25], v[12:13]
	v_add_f32_e32 v88, 1.0, v88
	v_add_f32_e32 v89, 1.0, v89
	v_exp_f32_e32 v90, v90
	v_exp_f32_e32 v91, v91
	v_pk_mul_f32 v[14:15], v[26:27], v[14:15]
	v_cvt_pk_bf16_f32 v78, v12, v13
	v_add_u32_e32 v12, 0x81, v194
	v_rcp_f32_e32 v88, v88
	v_rcp_f32_e32 v89, v89
	v_cvt_pk_bf16_f32 v79, v14, v15
	v_add_u32_e32 v14, s2, v12
	v_mov_b64_e32 v[12:13], s[88:89]
	v_pk_add_f32 v[16:17], v[52:53], v[16:17]
	v_pk_add_f32 v[18:19], v[54:55], v[18:19]
	v_mad_i64_i32 v[14:15], s[22:23], v14, s3, v[12:13]
	v_pk_mul_f32 v[24:25], v[0:1], v[40:41]
	v_mul_f32_e32 v20, 0xbfb8aa3b, v16
	v_mul_f32_e32 v21, 0xbfb8aa3b, v17
	v_mul_f32_e32 v22, 0xbfb8aa3b, v18
	v_mul_f32_e32 v23, 0xbfb8aa3b, v19
	v_lshl_add_u64 v[14:15], v[14:15], 0, v[70:71]
	v_pk_fma_f32 v[8:9], v[8:9], v[44:45], v[24:25]
	v_add_f32_e32 v90, 1.0, v90
	v_add_f32_e32 v91, 1.0, v91
	v_exp_f32_e32 v20, v20
	v_exp_f32_e32 v21, v21
	v_exp_f32_e32 v22, v22
	v_exp_f32_e32 v23, v23
	global_store_dwordx4 v[14:15], v[76:79], off nt
	v_pk_mul_f32 v[14:15], v[2:3], v[42:43]
	v_pk_fma_f32 v[8:9], v[4:5], v[36:37], v[8:9]
	v_rcp_f32_e32 v90, v90
	v_rcp_f32_e32 v91, v91
	v_pk_fma_f32 v[10:11], v[10:11], v[46:47], v[14:15]
	v_pk_add_f32 v[8:9], v[32:33], v[8:9]
	v_pk_mul_f32 v[14:15], v[28:29], v[88:89]
	v_add_f32_e32 v20, 1.0, v20
	v_pk_mul_f32 v[8:9], v[14:15], v[8:9]
	v_add_f32_e32 v21, 1.0, v21
	v_cvt_pk_bf16_f32 v74, v8, v9
	v_add_u32_e32 v8, s2, v195
	v_add_f32_e32 v22, 1.0, v22
	v_add_f32_e32 v23, 1.0, v23
	v_pk_fma_f32 v[10:11], v[6:7], v[38:39], v[10:11]
	v_mad_i64_i32 v[8:9], s[22:23], v8, s3, v[12:13]
	v_rcp_f32_e32 v20, v20
	v_rcp_f32_e32 v21, v21
	v_rcp_f32_e32 v22, v22
	v_rcp_f32_e32 v23, v23
	v_pk_add_f32 v[10:11], v[34:35], v[10:11]
	v_pk_mul_f32 v[24:25], v[30:31], v[90:91]
	v_lshl_add_u64 v[8:9], v[8:9], 0, v[70:71]
	v_pk_mul_f32 v[10:11], v[24:25], v[10:11]
	v_pk_mul_f32 v[6:7], v[6:7], v[42:43]
	v_cvt_pk_bf16_f32 v75, v10, v11
	global_store_dwordx4 v[8:9], v[72:75], off nt
	v_pk_mul_f32 v[4:5], v[4:5], v[40:41]
	v_pk_fma_f32 v[2:3], v[2:3], v[46:47], v[6:7]
	v_pk_fma_f32 v[0:1], v[0:1], v[44:45], v[4:5]
	v_pk_fma_f32 v[2:3], v[38:39], v[82:83], v[2:3]
	v_pk_fma_f32 v[0:1], v[36:37], v[80:81], v[0:1]
	v_pk_add_f32 v[2:3], v[34:35], v[2:3]
	v_pk_add_f32 v[0:1], v[32:33], v[0:1]
	v_pk_mul_f32 v[4:5], v[16:17], v[20:21]
	v_pk_mul_f32 v[6:7], v[18:19], v[22:23]
	v_pk_mul_f32 v[0:1], v[4:5], v[0:1]
	v_pk_mul_f32 v[2:3], v[6:7], v[2:3]
	v_cvt_pk_bf16_f32 v66, v0, v1
	s_nop 0
	v_cvt_pk_bf16_f32 v67, v2, v3
	s_and_saveexec_b64 s[22:23], s[56:57]
	s_cbranch_execz .LBB0_1191
	v_add_u32_e32 v2, s2, v214
	v_mov_b64_e32 v[0:1], s[88:89]
	v_mad_i64_i32 v[0:1], s[2:3], v2, s3, v[0:1]
	v_lshl_add_u64 v[0:1], v[188:189], 1, v[0:1]
	global_store_dwordx4 v[0:1], v[64:67], off nt
